# P2 NA strip prologue: the first unit's q loads issued ahead of the K/V ring fill (address needs only strip scalars), copied after the fill instead of loaded and waited for at loop entry
# baseline (speedup 1.0000x reference)
; __device__ __forceinline__ void na_strip(const Params& P, LAS unsigned char* lds, int strip, int hsel, int tid, int lane, int wave) {
;     ...
;         const int lo = na_start(r0, rows);
;         u32x4 kr[9], vr[9];
; #pragma unroll
;         for (int i = 0; i < 9; ++i) { const int row = min(lo + i, rows - 1); const size_t o = ((size_t)sq0 + (size_t)row * 64) * 512 + ssrc; kr[i] = *(const u32x4*)(KA + o); vr[i] = *(const u32x4*)(VA + o); }
;     ...
;     {   const size_t tq = (size_t)sq0 + (size_t)(r0 + rsel) * 64 + qc;
; #pragma unroll
;         for (int ks = 0; ks < 2; ++ks) qf[ks] = *(const bf16x8*)(QA + tq * 512 + h * 64 + 32 * ks + 8 * g); }
.LBB0_279:
	s_bitcmp1_b32 s74, 0
	s_cselect_b64 s[6:7], -1, 0
	s_and_b64 s[6:7], s[4:5], s[6:7]
	s_or_b32 s12, s11, 8
	s_and_b64 s[6:7], s[6:7], exec
	s_cselect_b32 s76, s12, s11
	v_sub_u32_e64 v2, s76, 4 clamp
	s_add_i32 s77, s75, -8
	v_readfirstlane_b32 s6, v2
	s_lshl_b32 s25, s10, 6
	s_min_u32 s17, s6, s77
	v_add_u32_e32 v70, s25, v79
	s_add_i32 s18, s75, -1
	s_lshl_b32 s48, s26, 9
	s_or_b32 s16, s17, 1
	v_lshl_add_u64 v[94:95], s[48:49], 0, v[70:71]
	s_min_u32 s48, s16, s18
	s_lshl_b64 s[6:7], s[48:49], 15
	v_lshl_add_u64 v[2:3], s[6:7], 0, v[94:95]
	s_or_b32 s15, s17, 2
	v_lshlrev_b64 v[2:3], 1, v[2:3]
	s_min_u32 s48, s15, s18
	v_lshl_add_u64 v[4:5], s[44:45], 0, v[2:3]
	v_lshl_add_u64 v[2:3], s[46:47], 0, v[2:3]
	s_lshl_b64 s[6:7], s[48:49], 15
	s_add_i32 s80, s76, s52
	s_mov_b32 s81, 0
	s_lshl_b64 s[80:81], s[80:81], 16
	s_add_u32 s80, s42, s80
	s_addc_u32 s81, s43, s81
	v_add_u32_e32 v242, s26, v103
	v_lshlrev_b32_e32 v242, 10, v242
	v_mov_b32_e32 v243, 0
	v_lshl_add_u64 v[242:243], s[80:81], 0, v[242:243]
	s_lshl_b32 s82, s25, 1
	s_mov_b32 s83, 0
	v_lshl_add_u64 v[242:243], v[242:243], 0, s[82:83]
	v_lshlrev_b32_e32 v244, 1, v68
	v_mov_b32_e32 v245, 0
	v_lshl_add_u64 v[242:243], v[242:243], 0, v[244:245]
	global_load_dwordx4 v[246:249], v[242:243], off offset:64
	global_load_dwordx4 v[242:245], v[242:243], off
	global_load_dwordx4 v[62:65], v[4:5], off
	global_load_dwordx4 v[58:61], v[2:3], off
	v_lshl_add_u64 v[2:3], s[6:7], 0, v[94:95]
	s_or_b32 s14, s17, 3
	v_lshlrev_b64 v[2:3], 1, v[2:3]
	s_min_u32 s48, s14, s18
	v_lshl_add_u64 v[4:5], s[44:45], 0, v[2:3]
	v_lshl_add_u64 v[2:3], s[46:47], 0, v[2:3]
	s_lshl_b64 s[6:7], s[48:49], 15
	global_load_dwordx4 v[54:57], v[4:5], off
	global_load_dwordx4 v[50:53], v[2:3], off
	v_lshl_add_u64 v[2:3], s[6:7], 0, v[94:95]
	s_add_i32 s13, s17, 4
	v_lshlrev_b64 v[2:3], 1, v[2:3]
	s_min_u32 s48, s13, s18
	v_lshl_add_u64 v[4:5], s[44:45], 0, v[2:3]
	v_lshl_add_u64 v[2:3], s[46:47], 0, v[2:3]
	s_lshl_b64 s[6:7], s[48:49], 15
	global_load_dwordx4 v[46:49], v[4:5], off
	global_load_dwordx4 v[42:45], v[2:3], off
	v_lshl_add_u64 v[2:3], s[6:7], 0, v[94:95]
	s_add_i32 s12, s17, 5
	v_lshlrev_b64 v[2:3], 1, v[2:3]
	s_min_u32 s48, s12, s18
	v_lshl_add_u64 v[4:5], s[44:45], 0, v[2:3]
	v_lshl_add_u64 v[2:3], s[46:47], 0, v[2:3]
	s_lshl_b64 s[6:7], s[48:49], 15
	global_load_dwordx4 v[38:41], v[4:5], off
	global_load_dwordx4 v[34:37], v[2:3], off
	v_lshl_add_u64 v[2:3], s[6:7], 0, v[94:95]
	s_add_i32 s11, s17, 6
	v_lshlrev_b64 v[2:3], 1, v[2:3]
	s_min_u32 s48, s11, s18
	v_lshl_add_u64 v[4:5], s[44:45], 0, v[2:3]
	v_lshl_add_u64 v[2:3], s[46:47], 0, v[2:3]
	s_lshl_b64 s[6:7], s[48:49], 15
	global_load_dwordx4 v[30:33], v[4:5], off
	global_load_dwordx4 v[26:29], v[2:3], off
	v_lshl_add_u64 v[2:3], s[6:7], 0, v[94:95]
	s_add_i32 s7, s17, 7
	v_lshlrev_b64 v[2:3], 1, v[2:3]
	s_min_u32 s48, s7, s18
	v_lshl_add_u64 v[4:5], s[44:45], 0, v[2:3]
	v_lshl_add_u64 v[2:3], s[46:47], 0, v[2:3]
	s_lshl_b64 s[20:21], s[48:49], 15
	global_load_dwordx4 v[22:25], v[4:5], off
	global_load_dwordx4 v[18:21], v[2:3], off
	v_lshl_add_u64 v[2:3], s[20:21], 0, v[94:95]
	s_add_i32 s6, s17, 8
	v_lshlrev_b64 v[2:3], 1, v[2:3]
	s_min_u32 s48, s6, s18
	v_lshl_add_u64 v[4:5], s[44:45], 0, v[2:3]
	v_lshl_add_u64 v[2:3], s[46:47], 0, v[2:3]
	s_lshl_b64 s[20:21], s[48:49], 15
	global_load_dwordx4 v[14:17], v[4:5], off
	global_load_dwordx4 v[10:13], v[2:3], off
	v_lshl_add_u64 v[2:3], s[20:21], 0, v[94:95]
	v_lshlrev_b64 v[2:3], 1, v[2:3]
	v_lshl_add_u64 v[4:5], s[44:45], 0, v[2:3]
	v_lshl_add_u64 v[2:3], s[46:47], 0, v[2:3]
	global_load_dwordx4 v[6:9], v[4:5], off
	s_nop 0
	global_load_dwordx4 v[2:5], v[2:3], off
	s_cmp_lt_u32 s17, s75
	s_cbranch_scc1 .LBB0_317
	s_cmp_ge_u32 s16, s75
	s_cbranch_scc0 .LBB0_318

; #define LAS __attribute__((address_space(3)))
; __device__ __forceinline__ void na_strip(const Params& P, LAS unsigned char* lds, int strip, int hsel, int tid, int lane, int wave) {
;     ...
;     const int rsel = wave >> 2, nb = wave & 3;
;     const int g = lane >> 4, l15 = lane & 15, q4 = l15 >> 2, p = lane & 3;
;     const int kstart = nb == 0 ? 0 : (nb == 1 ? 8 : (nb == 2 ? 24 : 32));
;     const int qc = 16 * nb + l15, wsq = min(max(qc - 8, 0), 48);
;     const LAS float* rp = (const LAS float*)(lds + NA_RPB);
;     float msk[2][4]; int bofs[2][4];
; #pragma unroll
;     for (int kt = 0; kt < 2; ++kt)
; #pragma unroll
;         for (int i = 0; i < 4; ++i) { const int kc = kstart + 16 * kt + 4 * g + i; msk[kt][i] = ((kc >= wsq) && (kc < wsq + 16)) ? -NA_SHIFT : -INFINITY; bofs[kt][i] = min(max(kc - qc + 15, 0), 30); }
;     bf16x8 qf[2];
;     {   const size_t tq = (size_t)sq0 + (size_t)(r0 + rsel) * 64 + qc;
; #pragma unroll
;         for (int ks = 0; ks < 2; ++ks) qf[ks] = *(const bf16x8*)(QA + tq * 512 + h * 64 + 32 * ks + 8 * g); }
.LBB0_295:
	s_and_b64 s[4:5], s[4:5], exec
	s_waitcnt vmcnt(0)
	v_add_u32_e32 v4, s27, v105
	v_cmp_ge_u32_e32 vcc, v4, v104
	v_cmp_lt_u32_e64 s[4:5], v4, v106
	v_or_b32_e32 v5, 1, v4
	s_cselect_b32 s34, 4, 8
	s_and_b64 vcc, vcc, s[4:5]
	v_cmp_ge_u32_e64 s[4:5], v5, v104
	v_cmp_lt_u32_e64 s[6:7], v5, v106
	v_or_b32_e32 v6, 2, v4
	s_and_b64 s[4:5], s[4:5], s[6:7]
	v_cmp_ge_u32_e64 s[6:7], v6, v104
	v_cmp_lt_u32_e64 s[10:11], v6, v106
	v_or_b32_e32 v7, 3, v4
	s_and_b64 s[6:7], s[6:7], s[10:11]
	v_cmp_ge_u32_e64 s[10:11], v7, v104
	v_cmp_lt_u32_e64 s[12:13], v7, v106
	v_add_u32_e32 v8, 16, v4
	s_and_b64 s[10:11], s[10:11], s[12:13]
	v_cmp_ge_u32_e64 s[12:13], v8, v104
	v_cmp_lt_u32_e64 s[14:15], v4, v104
	v_add_u32_e32 v9, 17, v4
	s_and_b64 s[12:13], s[12:13], s[14:15]
	v_cmp_ge_u32_e64 s[14:15], v9, v104
	v_cmp_lt_u32_e64 s[16:17], v9, v106
	v_add_u32_e32 v10, 18, v4
	s_and_b64 s[14:15], s[14:15], s[16:17]
	v_cmp_ge_u32_e64 s[16:17], v10, v104
	v_cmp_lt_u32_e64 s[18:19], v10, v106
	v_add_u32_e32 v11, 19, v4
	s_and_b64 s[16:17], s[16:17], s[18:19]
	v_cmp_ge_u32_e64 s[18:19], v11, v104
	v_cmp_lt_u32_e64 s[20:21], v11, v106
	s_add_i32 s48, s76, s52
	s_and_b64 s[18:19], s[18:19], s[20:21]
	s_lshl_b64 s[20:21], s[48:49], 16
	v_add_u32_e32 v46, s26, v103
	s_add_u32 s20, s42, s20
	v_lshlrev_b32_e32 v70, 10, v46
	s_addc_u32 s21, s43, s21
	v_lshl_add_u64 v[2:3], s[20:21], 0, v[70:71]
	s_lshl_b32 s20, s25, 1
	s_mov_b32 s21, s49
	v_lshl_add_u64 v[2:3], v[2:3], 0, s[20:21]
	v_lshlrev_b32_e32 v70, 1, v68
	v_lshl_add_u64 v[2:3], v[2:3], 0, v[70:71]
	v_mov_b32_e32 v30, v242
	v_mov_b32_e32 v31, v243
	v_mov_b32_e32 v32, v244
	v_mov_b32_e32 v33, v245
	v_mov_b32_e32 v26, v246
	v_mov_b32_e32 v27, v247
	v_mov_b32_e32 v28, v248
	v_mov_b32_e32 v29, v249
	v_sub_u32_e32 v2, v4, v103
	v_max_i32_e32 v2, -15, v2
	v_add_u32_e32 v2, 15, v2
	v_min_u32_e32 v63, 30, v2
	v_sub_u32_e32 v2, v5, v103
	v_max_i32_e32 v2, -15, v2
	v_add_u32_e32 v2, 15, v2
	v_min_u32_e32 v65, 30, v2
	v_sub_u32_e32 v2, v6, v103
	v_max_i32_e32 v2, -15, v2
	v_add_u32_e32 v2, 15, v2
	v_min_u32_e32 v96, 30, v2
	v_sub_u32_e32 v2, v7, v103
	v_max_i32_e32 v2, -15, v2
	v_add_u32_e32 v2, 15, v2
	v_min_u32_e32 v98, 30, v2
	v_sub_u32_e32 v2, v8, v103
	v_max_i32_e32 v2, -15, v2
	v_add_u32_e32 v2, 15, v2
	v_min_u32_e32 v100, 30, v2
	v_sub_u32_e32 v2, v9, v103
	v_max_i32_e32 v2, -15, v2
	v_add_u32_e32 v2, 15, v2
	v_or_b32_e32 v3, s27, v87
	v_min_u32_e32 v155, 30, v2
	v_sub_u32_e32 v2, v10, v103
	v_add_u32_e32 v3, v3, v105
	v_max_i32_e32 v2, -15, v2
	v_lshlrev_b32_e32 v4, 1, v3
	v_cndmask_b32_e64 v64, v147, v148, s[4:5]
	v_add_u32_e32 v2, 15, v2
	v_and_b32_e32 v5, 12, v4
	s_add_i32 s4, 0, 0x12000
	v_min_u32_e32 v157, 30, v2
	v_sub_u32_e32 v2, v11, v103
	v_lshl_add_u32 v160, v3, 7, s4
	v_or_b32_e32 v3, v5, v102
	v_max_i32_e32 v2, -15, v2
	v_lshlrev_b32_e32 v161, 3, v3
	v_bitop3_b32 v3, v4, v108, 12 bitop3:0x6c
	v_add_u32_e32 v2, 15, v2
	v_lshlrev_b32_e32 v162, 3, v3
	v_bitop3_b32 v3, v4, v109, 12 bitop3:0x6c
	v_min_u32_e32 v159, 30, v2
	v_add_u32_e32 v2, s27, v85
	v_lshlrev_b32_e32 v163, 3, v3
	v_bitop3_b32 v3, v4, v110, 12 bitop3:0x6c
	v_cndmask_b32_e32 v62, v147, v148, vcc
	v_cndmask_b32_e64 v93, v147, v148, s[6:7]
	v_cndmask_b32_e64 v97, v147, v148, s[10:11]
	v_cndmask_b32_e64 v99, v147, v148, s[12:13]
	v_cndmask_b32_e64 v101, v147, v148, s[14:15]
	v_cndmask_b32_e64 v156, v147, v148, s[16:17]
	v_cndmask_b32_e64 v158, v147, v148, s[18:19]
	v_mov_b32_e32 v47, v71
	s_add_i32 s18, s34, -1
	v_lshl_add_u64 v[48:49], v[72:73], 0, s[20:21]
	v_lshl_add_u64 v[50:51], v[74:75], 0, s[20:21]
	v_lshlrev_b32_e32 v164, 3, v3
	v_lshl_add_u32 v165, v2, 7, 0
	s_mov_b32 s19, 0
	s_sub_i32 s20, 0, s48
	s_lshl_b32 s10, s25, 1
	s_mov_b32 s21, s48
	s_waitcnt vmcnt(0)
	s_branch .LBB0_297
